# all_gemms_FR_P4_port
# speedup vs baseline: 1.0146x; 1.0013x over previous
; #define PG8_WAIT_V(n) asm volatile("s_waitcnt vmcnt(" #n ")" ::: "memory")
;     __host__ __device__ bool next(int i, Unit& u) const {
;         const long L = (long)i * G + c; if (L >= nwg) return false;
; template <class Epi, class Sched, bool ALIGN_EPI = false, bool SP2 = false>
; __device__ __forceinline__ void gemm_phase(PG8_LAS unsigned char* lds, const Gemm g, const Sched& S, const Epi& E) {
;     ...
;     for (int i = 0; i < 2; ++i) { int R, C; stage_rc(tid * 16 + i * 8192, R, C); const int Rb = Epi::PERM ? ((R & ~31) + perm32(R & 31)) : R;
;         voffA[i] = (unsigned)(R * K + C) * 2u; voffB[i] = (unsigned)(Rb * K + C) * 2u; }
;     const size_t kstep = (size_t)(BK * 2);
;     const size_t hstep = (size_t)HALF * K * 2;
;     const size_t tstep = 2 * hstep;
;     const unsigned ldsw = (unsigned)wid * 1024u;
;     const int aoff = lds_byte(wr * 64 + fr, fq * 8), boff = lds_byte(wc * 32 + fr, fq * 8);
;     ...
;     Unit cur, nxt; int ui = 0;
;     if (!S.next(0, cur)) return;
;     f32x4 acc[2][2][4][2];
; #pragma unroll
;     for (int a = 0; a < 2; ++a)
; #pragma unroll
;         for (int b = 0; b < 2; ++b)
; #pragma unroll
;             for (int m = 0; m < 4; ++m)
; #pragma unroll
;                 for (int n = 0; n < 2; ++n) acc[a][b][m][n] = (f32x4){0.f, 0.f, 0.f, 0.f};
;     bf16x8 At[4][2], B0[2][2], B1[2][2];
;     const char* cA = (const char*)g.A + (size_t)cur.pm * tstep; const char* cB = (const char*)g.Bt + (size_t)cur.pn * tstep;
;     S.a_ready(cur);
;     if constexpr (SP2) {
;         PG8_STAGE(PG8_SB(0, 0), cB, voffB); PG8_STAGE(PG8_SB(0, 1), cB + hstep, voffB); PG8_STAGE(PG8_SA(0, 0), cA, voffA); PG8_STAGE(PG8_SA(0, 1), cA + hstep, voffA);
;         if (wr == 1) PG8_BAR;
;         PG8_WAIT_V(2); PG8_BAR;
;         PG8_STAGE(PG8_SB(1, 0), cB + kstep, voffB); PG8_STAGE(PG8_SA(1, 0), cA + kstep, voffA); PG8_STAGE(PG8_SB(1, 1), cB + hstep + kstep, voffB);
;         PG8_WAIT_V(6); PG8_BAR;
;     } else {
;         PG8_STAGE(PG8_SB(0, 0), cB, voffB); PG8_STAGE(PG8_SA(0, 0), cA, voffA); PG8_STAGE(PG8_SB(0, 1), cB + hstep, voffB); PG8_STAGE(PG8_SA(0, 1), cA + hstep, voffA);
;         if (wr == 1) PG8_BAR;
;         PG8_WAIT_V(4); PG8_BAR;
;         PG8_STAGE(PG8_SB(1, 0), cB + kstep, voffB); PG8_STAGE(PG8_SA(1, 0), cA + kstep, voffA); PG8_STAGE(PG8_SB(1, 1), cB + hstep + kstep, voffB);
;         PG8_WAIT_V(6); PG8_BAR;
.LBB0_672:
	s_cmp_lt_i32 s70, 5
	s_cselect_b64 s[4:5], -1, 0
	s_and_b64 s[6:7], s[4:5], s[0:1]
	s_andn2_b64 vcc, exec, s[6:7]
	s_cbranch_vccnz .LBB0_715
	v_writelane_b32 v253, s4, 0
	v_writelane_b32 v253, s5, 1
	v_writelane_b32 v253, s6, 2
	v_writelane_b32 v253, s7, 3
	v_writelane_b32 v253, s8, 4
	v_writelane_b32 v253, s9, 5
	v_writelane_b32 v253, s10, 6
	v_writelane_b32 v253, s11, 7
	v_writelane_b32 v253, s12, 8
	v_writelane_b32 v253, s13, 9
	v_writelane_b32 v253, s14, 10
	v_writelane_b32 v253, s15, 11
	v_writelane_b32 v253, s16, 12
	v_writelane_b32 v253, s17, 13
	v_writelane_b32 v253, s18, 14
	v_writelane_b32 v253, s19, 15
	v_writelane_b32 v253, s20, 16
	v_writelane_b32 v253, s21, 17
	v_writelane_b32 v253, s22, 18
	v_writelane_b32 v253, s23, 19
	v_writelane_b32 v253, s24, 20
	v_writelane_b32 v253, s25, 21
	v_writelane_b32 v253, s26, 22
	v_writelane_b32 v253, s27, 23
	v_writelane_b32 v253, s28, 24
	v_writelane_b32 v253, s29, 25
	v_writelane_b32 v253, s30, 26
	v_writelane_b32 v253, s31, 27
	v_writelane_b32 v253, s32, 28
	v_writelane_b32 v253, s33, 29
	v_writelane_b32 v253, s34, 30
	v_writelane_b32 v253, s35, 31
	v_writelane_b32 v253, s36, 32
	v_writelane_b32 v253, s37, 33
	v_writelane_b32 v253, s38, 34
	v_writelane_b32 v253, s39, 35
	v_writelane_b32 v253, s40, 36
	v_writelane_b32 v253, s41, 37
	v_writelane_b32 v253, s42, 38
	v_writelane_b32 v253, s43, 39
	v_writelane_b32 v253, s44, 40
	v_writelane_b32 v253, s45, 41
	v_writelane_b32 v253, s46, 42
	v_writelane_b32 v253, s47, 43
	v_writelane_b32 v253, s48, 44
	v_writelane_b32 v253, s49, 45
	v_writelane_b32 v253, s50, 46
	v_writelane_b32 v253, s51, 47
	v_writelane_b32 v253, s52, 48
	v_writelane_b32 v253, s53, 49
	v_writelane_b32 v253, s54, 50
	v_writelane_b32 v253, s55, 51
	v_writelane_b32 v253, s56, 52
	v_writelane_b32 v253, s57, 53
	v_writelane_b32 v253, s58, 54
	v_writelane_b32 v253, s59, 55
	s_mov_b32 s40, vcc_lo
	s_mov_b32 s41, vcc_hi
	v_writelane_b32 v253, s40, 60
	v_writelane_b32 v253, s41, 61
	v_lshrrev_b32_e32 v254, 6, v185
	v_readlane_b32 s14, v244, 4
	v_readfirstlane_b32 s36, v254
	s_nop 3
	s_lshr_b32 s37, s36, 2
	s_and_b32 s38, s36, 3
	s_lshl_b32 s35, s36, 10
	s_add_u32 s10, s76, 0x18800000
	s_addc_u32 s11, s77, 0
	s_add_u32 s12, s76, 0x1d00000
	s_addc_u32 s13, s77, 0
	s_mov_b32 s16, 0
	s_mul_i32 s40, s16, s14
	s_add_u32 s40, s40, s2
	s_cmp_lt_u32 s40, 512
	s_cselect_b32 s44, 1, 0
	s_min_u32 s40, s40, 511
	s_and_b32 s41, s40, 7
	s_lshr_b32 s42, s40, 3
	s_mul_i32 s41, s41, 64
	s_add_u32 s41, s41, s42
	s_lshr_b32 s42, s41, 5
	s_and_b32 s43, s41, 31
	s_and_b32 s40, s43, 3
	s_lshl_b32 s42, s42, 2
	s_add_u32 s17, s42, s40
	s_lshr_b32 s18, s43, 2
	s_cmp_eq_u32 s44, 0
	s_cbranch_scc1 .Lp4_exit
	v_and_b32_e32 v254, 63, v185
	v_and_b32_e32 v255, 15, v254
	v_lshrrev_b32_e32 v186, 1, v255
	v_lshrrev_b32_e32 v187, 4, v254
	v_xor_b32_e32 v186, v186, v187
	v_lshlrev_b32_e32 v255, 7, v255
	v_lshl_or_b32 v255, v186, 4, v255
	s_lshl_b32 s40, s37, 13
	s_lshl_b32 s41, s38, 12
	s_add_u32 s41, s41, 0x10000
	v_add_u32_e32 v245, s40, v255
	v_add_u32_e32 v247, s41, v255
	v_xor_b32_e32 v246, 64, v245
	v_xor_b32_e32 v248, 64, v247
	v_lshrrev_b32_e32 v255, 3, v254
	v_and_b32_e32 v186, 7, v254
	s_and_b32 s40, s36, 1
	s_lshl_b32 s40, s40, 2
	v_lshrrev_b32_e32 v187, 1, v255
	v_add_u32_e32 v187, s40, v187
	v_xor_b32_e32 v186, v186, v187
	v_lshlrev_b32_e32 v186, 4, v186
	s_lshl_b32 s40, s36, 3
	v_add_u32_e32 v187, s40, v255
	v_mul_u32_u24_e32 v187, 0x1000, v187
	v_add_u32_e32 v249, v187, v186
	v_add_u32_e32 v250, 0x40000, v249
	s_and_b32 s40, s36, 3
	s_lshl_b32 s40, s40, 3
	v_add_u32_e32 v187, s40, v255
	v_lshrrev_b32_e32 v254, 4, v187
	v_lshlrev_b32_e32 v254, 2, v254
	v_and_b32_e32 v255, 3, v187
	v_add_u32_e32 v254, v254, v255
	v_and_b32_e32 v187, 12, v187
	v_lshl_add_u32 v254, v187, 1, v254
	s_lshr_b32 s40, s36, 2
	s_lshl_b32 s40, s40, 5
	v_add_u32_e32 v254, s40, v254
	v_mul_u32_u24_e32 v254, 0x1000, v254
	v_add_u32_e32 v251, v254, v186
	v_add_u32_e32 v252, 0x40000, v251
	s_mul_i32 s40, s17, 0x100000
	s_add_u32 s22, s10, s40
	s_addc_u32 s23, s11, 0
	s_mul_i32 s40, s18, 0x100000
	s_add_u32 s24, s12, s40
	s_addc_u32 s25, s13, 0
	s_and_b32 s40, s16, 1
	s_lshl_b32 s4, s40, 8
	s_sub_u32 s4, 128, s4
	s_sub_u32 s5, 0, s40
	s_mul_i32 s8, s40, 3968
	s_add_u32 s30, s22, s8
	s_addc_u32 s31, s23, 0
	s_add_u32 s32, s24, s8
	s_addc_u32 s33, s25, 0
	s_add_u32 s56, s30, 0x80000
	s_addc_u32 s57, s31, 0
	s_add_u32 s58, s32, 0x80000
	s_addc_u32 s59, s33, 0
	s_add_i32 m0, s35, 0x0
	s_nop 0
	global_load_lds_dwordx4 v249, s[30:31]
	s_add_i32 m0, s35, 0x2000
	s_nop 0
	global_load_lds_dwordx4 v250, s[30:31]
	s_add_i32 m0, s35, 0x10000
	s_nop 0
	global_load_lds_dwordx4 v251, s[32:33]
	s_add_i32 m0, s35, 0x12000
	s_nop 0
	global_load_lds_dwordx4 v252, s[32:33]
	s_add_i32 m0, s35, 0x4000
	s_nop 0
	global_load_lds_dwordx4 v249, s[56:57]
	s_add_i32 m0, s35, 0x6000
	s_nop 0
	global_load_lds_dwordx4 v250, s[56:57]
	s_add_i32 m0, s35, 0x14000
	s_nop 0
	global_load_lds_dwordx4 v251, s[58:59]
	s_add_i32 m0, s35, 0x16000
	s_nop 0
	global_load_lds_dwordx4 v252, s[58:59]
	s_add_u32 s30, s30, s4
	s_addc_u32 s31, s31, s5
	s_add_u32 s56, s56, s4
	s_addc_u32 s57, s57, s5
	s_add_u32 s32, s32, s4
	s_addc_u32 s33, s33, s5
	s_add_u32 s58, s58, s4
	s_addc_u32 s59, s59, s5
	s_add_i32 m0, s35, 0x8000
	s_nop 0
	global_load_lds_dwordx4 v249, s[30:31]
	s_add_i32 m0, s35, 0xa000
	s_nop 0
	global_load_lds_dwordx4 v250, s[30:31]
	s_add_i32 m0, s35, 0x1c000
	s_nop 0
	global_load_lds_dwordx4 v251, s[58:59]
	s_add_i32 m0, s35, 0x1e000
	s_nop 0
	global_load_lds_dwordx4 v252, s[58:59]
	s_add_i32 m0, s35, 0xc000
	s_nop 0
	global_load_lds_dwordx4 v249, s[56:57]
	s_add_i32 m0, s35, 0xe000
	s_nop 0
	global_load_lds_dwordx4 v250, s[56:57]
	s_add_i32 m0, s35, 0x18000
	s_nop 0
	global_load_lds_dwordx4 v251, s[32:33]
	s_add_i32 m0, s35, 0x1a000
	s_nop 0
	global_load_lds_dwordx4 v252, s[32:33]
	s_add_u32 s30, s30, s4
	s_addc_u32 s31, s31, s5
	s_add_u32 s56, s56, s4
	s_addc_u32 s57, s57, s5
	s_add_u32 s32, s32, s4
	s_addc_u32 s33, s33, s5
	s_add_u32 s58, s58, s4
	s_addc_u32 s59, s59, s5
	s_waitcnt vmcnt(12)
	s_barrier
; #define PG8_STAGE(bufoff, gbase, voff) do { _Pragma("unroll") for (int _i = 0; _i < 2; ++_i) \
;         __builtin_amdgcn_global_load_lds((const unsigned*)((const char*)(gbase) + (voff)[_i]), (PG8_LAS unsigned*)(lds + (bufoff) + ldsw + _i * 8192), 16, 0, 0); } while (0)
; #define PG8_LDA(dst, b, h) do { _Pragma("unroll") for (int m = 0; m < 4; ++m) _Pragma("unroll") for (int k = 0; k < 2; ++k) dst[m][k] = *(const PG8_LAS bf16x8*)(lds + PG8_SA(b, h) + aoff + m * 2048 + k * 1024); } while (0)
; #define PG8_LDB(dst, b, h) do { _Pragma("unroll") for (int n = 0; n < 2; ++n) _Pragma("unroll") for (int k = 0; k < 2; ++k) dst[n][k] = *(const PG8_LAS bf16x8*)(lds + PG8_SB(b, h) + boff + n * 2048 + k * 1024); } while (0)
; #define PG8_SCHED __builtin_amdgcn_sched_barrier(0)
;     __host__ __device__ bool next(int i, Unit& u) const {
;         const long L = (long)i * G + c; if (L >= nwg) return false;
;         int wgid = (int)L; { const int q = nwg / NXCD, r = nwg % NXCD, xcd = wgid % NXCD, off = wgid / NXCD; wgid = (xcd < r ? xcd * (q + 1) : r * (q + 1) + (xcd - r) * q) + off; }
;         const int nig = wgm * nN, gid = wgid / nig, fm = gid * wgm, gsz = (nM - fm) < wgm ? (nM - fm) : wgm;
;         u.pm = fm + ((wgid % nig) % gsz); u.pn = (wgid % nig) / gsz; return true;
; template <class Epi, class Sched, bool ALIGN_EPI = false, bool SP2 = false>
; __device__ __forceinline__ void gemm_phase(PG8_LAS unsigned char* lds, const Gemm g, const Sched& S, const Epi& E) {
;     ...
;         const bool has_next = S.next(ui + 1, nxt);
;         const char* nA = has_next ? (const char*)g.A + (size_t)nxt.pm * tstep : cA; const char* nB = has_next ? (const char*)g.Bt + (size_t)nxt.pn * tstep : cB;
;         for (int t = 0; t < nt; t += 2) {
;             const bool last = (t == nt - 2);
;             const char* a1 = cA + (size_t)(t + 1) * kstep;
;             const char* a2 = last ? nA : cA + (size_t)(t + 2) * kstep; const char* b2 = last ? nB : cB + (size_t)(t + 2) * kstep;
;             const char* a3 = a2 + kstep; const char* b3 = b2 + kstep;
;             if (last && has_next) S.a_ready(nxt);
;             if constexpr (SP2) {
;             PG8_LDB(B0, 0, 0); PG8_LDB(B1, 0, 1); PG8_SCHED; PG8_LDA(At, 0, 0); PG8_STAGE(PG8_SA(1, 1), a1 + hstep, voffA);
.Lp4_unit:
	s_add_u32 s45, s16, 1
	s_mul_i32 s40, s45, s14
	s_add_u32 s40, s40, s2
	s_cmp_lt_u32 s40, 512
	s_cselect_b32 s19, 1, 0
	s_min_u32 s40, s40, 511
	s_and_b32 s41, s40, 7
	s_lshr_b32 s42, s40, 3
	s_mul_i32 s41, s41, 64
	s_add_u32 s41, s41, s42
	s_lshr_b32 s42, s41, 5
	s_and_b32 s43, s41, 31
	s_and_b32 s40, s43, 3
	s_lshl_b32 s42, s42, 2
	s_add_u32 s20, s42, s40
	s_lshr_b32 s21, s43, 2
	s_mul_i32 s40, s20, 0x100000
	s_add_u32 s26, s10, s40
	s_addc_u32 s27, s11, 0
	s_mul_i32 s40, s21, 0x100000
	s_add_u32 s28, s12, s40
	s_addc_u32 s29, s13, 0
	s_cmp_eq_u32 s19, 0
	s_cselect_b32 s26, s22, s26
	s_cselect_b32 s27, s23, s27
	s_cselect_b32 s28, s24, s28
	s_cselect_b32 s29, s25, s29
	s_add_u32 s30, s22, s8
	s_addc_u32 s31, s23, 0
	s_add_u32 s32, s24, s8
	s_addc_u32 s33, s25, 0
	s_add_u32 s30, s30, s4
	s_addc_u32 s31, s31, s5
	s_add_u32 s32, s32, s4
	s_addc_u32 s33, s33, s5
	s_add_u32 s30, s30, s4
	s_addc_u32 s31, s31, s5
	s_add_u32 s32, s32, s4
	s_addc_u32 s33, s33, s5
	s_add_u32 s56, s30, 0x80000
	s_addc_u32 s57, s31, 0
	s_add_u32 s58, s32, 0x80000
	s_addc_u32 s59, s33, 0
	s_movk_i32 s34, 16
	v_mov_b32_e32 v0, 0
	v_mov_b32_e32 v1, 0
	v_mov_b32_e32 v2, 0
	v_mov_b32_e32 v3, 0
	v_mov_b32_e32 v4, 0
	v_mov_b32_e32 v5, 0
	v_mov_b32_e32 v6, 0
	v_mov_b32_e32 v7, 0
	v_mov_b32_e32 v8, 0
	v_mov_b32_e32 v9, 0
	v_mov_b32_e32 v10, 0
	v_mov_b32_e32 v11, 0
	v_mov_b32_e32 v12, 0
	v_mov_b32_e32 v13, 0
	v_mov_b32_e32 v14, 0
	v_mov_b32_e32 v15, 0
	v_mov_b32_e32 v16, 0
	v_mov_b32_e32 v17, 0
	v_mov_b32_e32 v18, 0
	v_mov_b32_e32 v19, 0
	v_mov_b32_e32 v20, 0
	v_mov_b32_e32 v21, 0
	v_mov_b32_e32 v22, 0
	v_mov_b32_e32 v23, 0
	v_mov_b32_e32 v24, 0
	v_mov_b32_e32 v25, 0
	v_mov_b32_e32 v26, 0
	v_mov_b32_e32 v27, 0
	v_mov_b32_e32 v28, 0
	v_mov_b32_e32 v29, 0
	v_mov_b32_e32 v30, 0
	v_mov_b32_e32 v31, 0
	v_mov_b32_e32 v32, 0
	v_mov_b32_e32 v33, 0
	v_mov_b32_e32 v34, 0
	v_mov_b32_e32 v35, 0
	v_mov_b32_e32 v36, 0
	v_mov_b32_e32 v37, 0
	v_mov_b32_e32 v38, 0
	v_mov_b32_e32 v39, 0
	v_mov_b32_e32 v40, 0
	v_mov_b32_e32 v41, 0
	v_mov_b32_e32 v42, 0
	v_mov_b32_e32 v43, 0
	v_mov_b32_e32 v44, 0
	v_mov_b32_e32 v45, 0
	v_mov_b32_e32 v46, 0
	v_mov_b32_e32 v47, 0
	v_mov_b32_e32 v48, 0
	v_mov_b32_e32 v49, 0
	v_mov_b32_e32 v50, 0
	v_mov_b32_e32 v51, 0
	v_mov_b32_e32 v52, 0
	v_mov_b32_e32 v53, 0
	v_mov_b32_e32 v54, 0
	v_mov_b32_e32 v55, 0
	v_mov_b32_e32 v56, 0
	v_mov_b32_e32 v57, 0
	v_mov_b32_e32 v58, 0
	v_mov_b32_e32 v59, 0
	v_mov_b32_e32 v60, 0
	v_mov_b32_e32 v61, 0
	v_mov_b32_e32 v62, 0
	v_mov_b32_e32 v63, 0
	v_mov_b32_e32 v64, 0
	v_mov_b32_e32 v65, 0
	v_mov_b32_e32 v66, 0
	v_mov_b32_e32 v67, 0
	v_mov_b32_e32 v68, 0
	v_mov_b32_e32 v69, 0
	v_mov_b32_e32 v70, 0
	v_mov_b32_e32 v71, 0
	v_mov_b32_e32 v72, 0
	v_mov_b32_e32 v73, 0
	v_mov_b32_e32 v74, 0
	v_mov_b32_e32 v75, 0
	v_mov_b32_e32 v76, 0
	v_mov_b32_e32 v77, 0
	v_mov_b32_e32 v78, 0
	v_mov_b32_e32 v79, 0
	v_mov_b32_e32 v80, 0
	v_mov_b32_e32 v81, 0
	v_mov_b32_e32 v82, 0
	v_mov_b32_e32 v83, 0
	v_mov_b32_e32 v84, 0
	v_mov_b32_e32 v85, 0
	v_mov_b32_e32 v86, 0
	v_mov_b32_e32 v87, 0
	v_mov_b32_e32 v88, 0
	v_mov_b32_e32 v89, 0
	v_mov_b32_e32 v90, 0
	v_mov_b32_e32 v91, 0
	v_mov_b32_e32 v92, 0
	v_mov_b32_e32 v93, 0
	v_mov_b32_e32 v94, 0
	v_mov_b32_e32 v95, 0
	v_mov_b32_e32 v96, 0
	v_mov_b32_e32 v97, 0
	v_mov_b32_e32 v98, 0
	v_mov_b32_e32 v99, 0
	v_mov_b32_e32 v100, 0
	v_mov_b32_e32 v101, 0
	v_mov_b32_e32 v102, 0
	v_mov_b32_e32 v103, 0
	v_mov_b32_e32 v104, 0
	v_mov_b32_e32 v105, 0
	v_mov_b32_e32 v106, 0
	v_mov_b32_e32 v107, 0
	v_mov_b32_e32 v108, 0
	v_mov_b32_e32 v109, 0
	v_mov_b32_e32 v110, 0
	v_mov_b32_e32 v111, 0
	v_mov_b32_e32 v112, 0
	v_mov_b32_e32 v113, 0
	v_mov_b32_e32 v114, 0
	v_mov_b32_e32 v115, 0
	v_mov_b32_e32 v116, 0
	v_mov_b32_e32 v117, 0
	v_mov_b32_e32 v118, 0
	v_mov_b32_e32 v119, 0
	v_mov_b32_e32 v120, 0
	v_mov_b32_e32 v121, 0
	v_mov_b32_e32 v122, 0
	v_mov_b32_e32 v123, 0
	v_mov_b32_e32 v124, 0
	v_mov_b32_e32 v125, 0
	v_mov_b32_e32 v126, 0
	v_mov_b32_e32 v127, 0
	ds_read_b128 v[196:199], v247 offset:0
	ds_read_b128 v[200:203], v248 offset:0
	ds_read_b128 v[204:207], v247 offset:2048
	ds_read_b128 v[208:211], v248 offset:2048
	ds_read_b128 v[128:131], v245 offset:0
	ds_read_b128 v[132:135], v246 offset:0
	ds_read_b128 v[136:139], v245 offset:2048
	ds_read_b128 v[140:143], v246 offset:2048
	ds_read_b128 v[144:147], v245 offset:4096
	ds_read_b128 v[148:151], v246 offset:4096
	ds_read_b128 v[152:155], v245 offset:6144
	ds_read_b128 v[156:159], v246 offset:6144
	s_cmp_ge_u32 s36, 4
	s_cbranch_scc1 .Lp4_kloop1

;     __device__ __forceinline__ void tail(const f32x4& b0, const f32x4& b1, const f32x4& a0, const f32x4& a1, bf16_t* dst, float& s) const {
;         const f32x4 o0 = b0 + a0, o1 = b1 + a1;
;         s += ((o0[0] * o0[0] + o0[1] * o0[1]) + (o0[2] * o0[2] + o0[3] * o0[3])) + ((o1[0] * o1[0] + o1[1] * o1[1]) + (o1[2] * o1[2] + o1[3] * o1[3]));
;         u32x4 w; w.x = cvt_pk_bf16(o0[0], o0[1]); w.y = cvt_pk_bf16(o0[2], o0[3]); w.z = cvt_pk_bf16(o1[0], o1[1]); w.w = cvt_pk_bf16(o1[2], o1[3]);
;         *(u32x4*)dst = w;
;     }
;     __device__ __forceinline__ void operator()(const f32x4 (&acc)[2][2][4][2], const Unit& u, int wr, int wc, int fr, int fq) const {
;         const int col0 = u.pn * BM + wc * 32 + 8 * fq;
;         if constexpr (BASE_BF16) {
;             u32x4 raw[2][4][2];
; #pragma unroll
;             for (int ai = 0; ai < 2; ++ai)
; #pragma unroll
;                 for (int m = 0; m < 4; ++m) { const int row = u.pm * BM + ai * HALF + wr * 64 + m * 16 + fr; const size_t off = (size_t)row * ldc + col0;
; #pragma unroll
;                     for (int bj = 0; bj < 2; ++bj) raw[ai][m][bj] = *(const u32x4*)((const bf16_t*)base + off + bj * HALF); }
;             asm volatile("" ::: "memory");
; #pragma unroll
;             for (int ai = 0; ai < 2; ++ai)
; #pragma unroll
;                 for (int m = 0; m < 4; ++m) { const int row = u.pm * BM + ai * HALF + wr * 64 + m * 16 + fr; const size_t off = (size_t)row * ldc + col0; float s = 0.f;
; #pragma unroll
;                     for (int bj = 0; bj < 2; ++bj) { const u32x4 r = raw[ai][m][bj];
;                         const f32x4 b0 = {__uint_as_float(r.x << 16), __uint_as_float(r.x & 0xffff0000u), __uint_as_float(r.y << 16), __uint_as_float(r.y & 0xffff0000u)};
;                         const f32x4 b1 = {__uint_as_float(r.z << 16), __uint_as_float(r.z & 0xffff0000u), __uint_as_float(r.w << 16), __uint_as_float(r.w & 0xffff0000u)};
;                         tail(b0, b1, acc[ai][bj][m][0], acc[ai][bj][m][1], out + off + bj * HALF, s); }
;                     s += __shfl_xor(s, 16); s += __shfl_xor(s, 32);
;                     if (fq == 0) atomicAdd(ss + row, s); }
;         } else {
;             f32x4 qa0[2][2], qa1[2][2], qb0[2][2], qb1[2][2];
;     ...
;             EPI_LDQ(qa0, qa1, 0); EPI_LDQ(qb0, qb1, 1); asm volatile("" ::: "memory");
.Lp4_kdone:
	s_waitcnt lgkmcnt(0)
	s_nop 7
	s_nop 7
	v_and_b32_e32 v254, 63, v185
	v_and_b32_e32 v255, 15, v254
	v_lshrrev_b32_e32 v233, 4, v254
	s_lshl_b32 s40, s37, 6
	v_add_u32_e32 v255, s40, v255
	v_lshlrev_b32_e32 v230, 2, v255
	v_lshlrev_b32_e32 v228, 13, v255
	v_lshlrev_b32_e32 v229, 12, v255
	s_lshl_b32 s41, s38, 7
	v_lshl_add_u32 v228, v233, 5, v228
	v_add_u32_e32 v228, s41, v228
	s_lshl_b32 s41, s38, 6
	v_lshl_add_u32 v229, v233, 4, v229
	v_add_u32_e32 v229, s41, v229
	v_xor_b32_e32 v231, 16, v254
	v_lshlrev_b32_e32 v231, 2, v231
	v_xor_b32_e32 v232, 32, v254
	v_lshlrev_b32_e32 v232, 2, v232
	v_readlane_b32 s48, v244, 12
	v_readlane_b32 s49, v244, 13
	s_lshl_b32 s40, s17, 21
	s_lshl_b32 s41, s18, 10
	s_add_u32 s40, s40, s41
	s_add_u32 s48, s48, s40
	s_addc_u32 s49, s49, 0
	s_lshl_b32 s40, s17, 10
	s_add_u32 s50, s76, s40
	s_addc_u32 s51, s77, 0
	s_lshl_b32 s40, s17, 20
	s_lshl_b32 s41, s18, 9
	s_add_u32 s40, s40, s41
	s_add_u32 s52, s76, 0x6800000
	s_addc_u32 s53, s77, 0
	s_add_u32 s52, s52, s40
	s_addc_u32 s53, s53, 0
	v_add_u32_e32 v233, 0x0, v228
	global_load_dwordx4 v[128:131], v233, s[48:49] offset:0
	global_load_dwordx4 v[132:135], v233, s[48:49] offset:16
	global_load_dwordx4 v[136:139], v233, s[48:49] offset:512
	global_load_dwordx4 v[140:143], v233, s[48:49] offset:528
	v_add_u32_e32 v233, 0x20000, v228
	global_load_dwordx4 v[144:147], v233, s[48:49] offset:0
	global_load_dwordx4 v[148:151], v233, s[48:49] offset:16
	global_load_dwordx4 v[152:155], v233, s[48:49] offset:512
	global_load_dwordx4 v[156:159], v233, s[48:49] offset:528
	v_add_u32_e32 v233, 0x40000, v228
	global_load_dwordx4 v[160:163], v233, s[48:49] offset:0
	global_load_dwordx4 v[164:167], v233, s[48:49] offset:16
	global_load_dwordx4 v[168:171], v233, s[48:49] offset:512
	global_load_dwordx4 v[172:175], v233, s[48:49] offset:528
	v_add_u32_e32 v233, 0x60000, v228
	global_load_dwordx4 v[176:179], v233, s[48:49] offset:0
	global_load_dwordx4 v[180:183], v233, s[48:49] offset:16
	global_load_dwordx4 v[188:191], v233, s[48:49] offset:512
	global_load_dwordx4 v[192:195], v233, s[48:49] offset:528
	v_add_u32_e32 v233, 0x100000, v228
	global_load_dwordx4 v[196:199], v233, s[48:49] offset:0
	global_load_dwordx4 v[200:203], v233, s[48:49] offset:16
	global_load_dwordx4 v[204:207], v233, s[48:49] offset:512
	global_load_dwordx4 v[208:211], v233, s[48:49] offset:528
	v_add_u32_e32 v233, 0x120000, v228
	global_load_dwordx4 v[212:215], v233, s[48:49] offset:0
	global_load_dwordx4 v[216:219], v233, s[48:49] offset:16
	global_load_dwordx4 v[220:223], v233, s[48:49] offset:512
	global_load_dwordx4 v[224:227], v233, s[48:49] offset:528
	s_waitcnt vmcnt(16)
	v_add_f32_e32 v0, v0, v128
	v_mul_f32_e32 v235, v0, v0
	v_add_f32_e32 v1, v1, v129
	v_fmac_f32_e32 v235, v1, v1
	v_add_f32_e32 v2, v2, v130
	v_fmac_f32_e32 v235, v2, v2
	v_add_f32_e32 v3, v3, v131
	v_fmac_f32_e32 v235, v3, v3
	v_add_f32_e32 v4, v4, v132
	v_fmac_f32_e32 v235, v4, v4
	v_add_f32_e32 v5, v5, v133
	v_fmac_f32_e32 v235, v5, v5
	v_add_f32_e32 v6, v6, v134
	v_fmac_f32_e32 v235, v6, v6
	v_add_f32_e32 v7, v7, v135
	v_fmac_f32_e32 v235, v7, v7
	v_add_f32_e32 v32, v32, v136
	v_fmac_f32_e32 v235, v32, v32
	v_add_f32_e32 v33, v33, v137
	v_fmac_f32_e32 v235, v33, v33
	v_add_f32_e32 v34, v34, v138
	v_fmac_f32_e32 v235, v34, v34
	v_add_f32_e32 v35, v35, v139
	v_fmac_f32_e32 v235, v35, v35
	v_add_f32_e32 v36, v36, v140
	v_fmac_f32_e32 v235, v36, v36
	v_add_f32_e32 v37, v37, v141
	v_fmac_f32_e32 v235, v37, v37
	v_add_f32_e32 v38, v38, v142
	v_fmac_f32_e32 v235, v38, v38
	v_add_f32_e32 v39, v39, v143
	v_fmac_f32_e32 v235, v39, v39
	v_add_u32_e32 v234, 0x0, v229
	v_cvt_pk_bf16_f32 v0, v0, v1
	v_cvt_pk_bf16_f32 v1, v2, v3
	v_cvt_pk_bf16_f32 v2, v4, v5
	v_cvt_pk_bf16_f32 v3, v6, v7
	s_nop 1
	global_store_dwordx4 v234, v[0:3], s[52:53] offset:0
	v_cvt_pk_bf16_f32 v32, v32, v33
	v_cvt_pk_bf16_f32 v33, v34, v35
	v_cvt_pk_bf16_f32 v34, v36, v37
	v_cvt_pk_bf16_f32 v35, v38, v39
	s_nop 1
	global_store_dwordx4 v234, v[32:35], s[52:53] offset:256
	v_mov_b32_e32 v36, v235
	v_add_f32_e32 v8, v8, v144
	v_mul_f32_e32 v235, v8, v8
	v_add_f32_e32 v9, v9, v145
	v_fmac_f32_e32 v235, v9, v9
	v_add_f32_e32 v10, v10, v146
	v_fmac_f32_e32 v235, v10, v10
	v_add_f32_e32 v11, v11, v147
	v_fmac_f32_e32 v235, v11, v11
	v_add_f32_e32 v12, v12, v148
	v_fmac_f32_e32 v235, v12, v12
	v_add_f32_e32 v13, v13, v149
	v_fmac_f32_e32 v235, v13, v13
	v_add_f32_e32 v14, v14, v150
	v_fmac_f32_e32 v235, v14, v14
	v_add_f32_e32 v15, v15, v151
	v_fmac_f32_e32 v235, v15, v15
	v_add_f32_e32 v40, v40, v152
	v_fmac_f32_e32 v235, v40, v40
	v_add_f32_e32 v41, v41, v153
	v_fmac_f32_e32 v235, v41, v41
	v_add_f32_e32 v42, v42, v154
	v_fmac_f32_e32 v235, v42, v42
	v_add_f32_e32 v43, v43, v155
	v_fmac_f32_e32 v235, v43, v43
	v_add_f32_e32 v44, v44, v156
	v_fmac_f32_e32 v235, v44, v44
	v_add_f32_e32 v45, v45, v157
	v_fmac_f32_e32 v235, v45, v45
	v_add_f32_e32 v46, v46, v158
	v_fmac_f32_e32 v235, v46, v46
	v_add_f32_e32 v47, v47, v159
	v_fmac_f32_e32 v235, v47, v47
	v_add_u32_e32 v234, 0x10000, v229
	v_cvt_pk_bf16_f32 v8, v8, v9
	v_cvt_pk_bf16_f32 v9, v10, v11
	v_cvt_pk_bf16_f32 v10, v12, v13
	v_cvt_pk_bf16_f32 v11, v14, v15
	s_nop 1
	global_store_dwordx4 v234, v[8:11], s[52:53] offset:0
	v_cvt_pk_bf16_f32 v40, v40, v41
	v_cvt_pk_bf16_f32 v41, v42, v43
	v_cvt_pk_bf16_f32 v42, v44, v45
	v_cvt_pk_bf16_f32 v43, v46, v47
	s_nop 1
	global_store_dwordx4 v234, v[40:43], s[52:53] offset:256
	v_mov_b32_e32 v44, v235
	v_add_u32_e32 v233, 0x140000, v228
	global_load_dwordx4 v[128:131], v233, s[48:49] offset:0
	global_load_dwordx4 v[132:135], v233, s[48:49] offset:16
	global_load_dwordx4 v[136:139], v233, s[48:49] offset:512
	global_load_dwordx4 v[140:143], v233, s[48:49] offset:528
	v_add_u32_e32 v233, 0x160000, v228
	global_load_dwordx4 v[144:147], v233, s[48:49] offset:0
	global_load_dwordx4 v[148:151], v233, s[48:49] offset:16
	global_load_dwordx4 v[152:155], v233, s[48:49] offset:512
	global_load_dwordx4 v[156:159], v233, s[48:49] offset:528
	s_waitcnt vmcnt(20)
;     __device__ __forceinline__ void tail(const f32x4& b0, const f32x4& b1, const f32x4& a0, const f32x4& a1, bf16_t* dst, float& s) const {
;         const f32x4 o0 = b0 + a0, o1 = b1 + a1;
;         s += ((o0[0] * o0[0] + o0[1] * o0[1]) + (o0[2] * o0[2] + o0[3] * o0[3])) + ((o1[0] * o1[0] + o1[1] * o1[1]) + (o1[2] * o1[2] + o1[3] * o1[3]));
;         u32x4 w; w.x = cvt_pk_bf16(o0[0], o0[1]); w.y = cvt_pk_bf16(o0[2], o0[3]); w.z = cvt_pk_bf16(o1[0], o1[1]); w.w = cvt_pk_bf16(o1[2], o1[3]);
;         *(u32x4*)dst = w;
;     }
;     __device__ __forceinline__ void operator()(const f32x4 (&acc)[2][2][4][2], const Unit& u, int wr, int wc, int fr, int fq) const {
;         const int col0 = u.pn * BM + wc * 32 + 8 * fq;
;         if constexpr (BASE_BF16) {
;             u32x4 raw[2][4][2];
; #pragma unroll
;             for (int ai = 0; ai < 2; ++ai)
; #pragma unroll
;                 for (int m = 0; m < 4; ++m) { const int row = u.pm * BM + ai * HALF + wr * 64 + m * 16 + fr; const size_t off = (size_t)row * ldc + col0;
; #pragma unroll
;                     for (int bj = 0; bj < 2; ++bj) raw[ai][m][bj] = *(const u32x4*)((const bf16_t*)base + off + bj * HALF); }
;             asm volatile("" ::: "memory");
; #pragma unroll
;             for (int ai = 0; ai < 2; ++ai)
; #pragma unroll
;                 for (int m = 0; m < 4; ++m) { const int row = u.pm * BM + ai * HALF + wr * 64 + m * 16 + fr; const size_t off = (size_t)row * ldc + col0; float s = 0.f;
; #pragma unroll
;                     for (int bj = 0; bj < 2; ++bj) { const u32x4 r = raw[ai][m][bj];
;                         const f32x4 b0 = {__uint_as_float(r.x << 16), __uint_as_float(r.x & 0xffff0000u), __uint_as_float(r.y << 16), __uint_as_float(r.y & 0xffff0000u)};
;                         const f32x4 b1 = {__uint_as_float(r.z << 16), __uint_as_float(r.z & 0xffff0000u), __uint_as_float(r.w << 16), __uint_as_float(r.w & 0xffff0000u)};
;                         tail(b0, b1, acc[ai][bj][m][0], acc[ai][bj][m][1], out + off + bj * HALF, s); }
;                     s += __shfl_xor(s, 16); s += __shfl_xor(s, 32);
;                     if (fq == 0) atomicAdd(ss + row, s); }
;         } else {
;             f32x4 qa0[2][2], qa1[2][2], qb0[2][2], qb1[2][2];
;     ...
;             EPI_LDQ(qa0, qa1, 0); EPI_LDQ(qb0, qb1, 1); asm volatile("" ::: "memory");
	v_add_f32_e32 v16, v16, v160
	v_mul_f32_e32 v235, v16, v16
	v_add_f32_e32 v17, v17, v161
	v_fmac_f32_e32 v235, v17, v17
	v_add_f32_e32 v18, v18, v162
	v_fmac_f32_e32 v235, v18, v18
	v_add_f32_e32 v19, v19, v163
	v_fmac_f32_e32 v235, v19, v19
	v_add_f32_e32 v20, v20, v164
	v_fmac_f32_e32 v235, v20, v20
	v_add_f32_e32 v21, v21, v165
	v_fmac_f32_e32 v235, v21, v21
	v_add_f32_e32 v22, v22, v166
	v_fmac_f32_e32 v235, v22, v22
	v_add_f32_e32 v23, v23, v167
	v_fmac_f32_e32 v235, v23, v23
	v_add_f32_e32 v48, v48, v168
	v_fmac_f32_e32 v235, v48, v48
	v_add_f32_e32 v49, v49, v169
	v_fmac_f32_e32 v235, v49, v49
	v_add_f32_e32 v50, v50, v170
	v_fmac_f32_e32 v235, v50, v50
	v_add_f32_e32 v51, v51, v171
	v_fmac_f32_e32 v235, v51, v51
	v_add_f32_e32 v52, v52, v172
	v_fmac_f32_e32 v235, v52, v52
	v_add_f32_e32 v53, v53, v173
	v_fmac_f32_e32 v235, v53, v53
	v_add_f32_e32 v54, v54, v174
	v_fmac_f32_e32 v235, v54, v54
	v_add_f32_e32 v55, v55, v175
	v_fmac_f32_e32 v235, v55, v55
	v_add_u32_e32 v234, 0x20000, v229
	v_cvt_pk_bf16_f32 v16, v16, v17
	v_cvt_pk_bf16_f32 v17, v18, v19
	v_cvt_pk_bf16_f32 v18, v20, v21
	v_cvt_pk_bf16_f32 v19, v22, v23
	s_nop 1
	global_store_dwordx4 v234, v[16:19], s[52:53] offset:0
	v_cvt_pk_bf16_f32 v48, v48, v49
	v_cvt_pk_bf16_f32 v49, v50, v51
	v_cvt_pk_bf16_f32 v50, v52, v53
	v_cvt_pk_bf16_f32 v51, v54, v55
	s_nop 1
	global_store_dwordx4 v234, v[48:51], s[52:53] offset:256
	v_mov_b32_e32 v52, v235
	v_add_f32_e32 v24, v24, v176
	v_mul_f32_e32 v235, v24, v24
	v_add_f32_e32 v25, v25, v177
	v_fmac_f32_e32 v235, v25, v25
	v_add_f32_e32 v26, v26, v178
	v_fmac_f32_e32 v235, v26, v26
	v_add_f32_e32 v27, v27, v179
	v_fmac_f32_e32 v235, v27, v27
	v_add_f32_e32 v28, v28, v180
	v_fmac_f32_e32 v235, v28, v28
	v_add_f32_e32 v29, v29, v181
	v_fmac_f32_e32 v235, v29, v29
	v_add_f32_e32 v30, v30, v182
	v_fmac_f32_e32 v235, v30, v30
	v_add_f32_e32 v31, v31, v183
	v_fmac_f32_e32 v235, v31, v31
	v_add_f32_e32 v56, v56, v188
	v_fmac_f32_e32 v235, v56, v56
	v_add_f32_e32 v57, v57, v189
	v_fmac_f32_e32 v235, v57, v57
	v_add_f32_e32 v58, v58, v190
	v_fmac_f32_e32 v235, v58, v58
	v_add_f32_e32 v59, v59, v191
	v_fmac_f32_e32 v235, v59, v59
	v_add_f32_e32 v60, v60, v192
	v_fmac_f32_e32 v235, v60, v60
	v_add_f32_e32 v61, v61, v193
	v_fmac_f32_e32 v235, v61, v61
	v_add_f32_e32 v62, v62, v194
	v_fmac_f32_e32 v235, v62, v62
	v_add_f32_e32 v63, v63, v195
	v_fmac_f32_e32 v235, v63, v63
	v_add_u32_e32 v234, 0x30000, v229
	v_cvt_pk_bf16_f32 v24, v24, v25
	v_cvt_pk_bf16_f32 v25, v26, v27
	v_cvt_pk_bf16_f32 v26, v28, v29
	v_cvt_pk_bf16_f32 v27, v30, v31
	s_nop 1
	global_store_dwordx4 v234, v[24:27], s[52:53] offset:0
	v_cvt_pk_bf16_f32 v56, v56, v57
	v_cvt_pk_bf16_f32 v57, v58, v59
	v_cvt_pk_bf16_f32 v58, v60, v61
	v_cvt_pk_bf16_f32 v59, v62, v63
	s_nop 1
	global_store_dwordx4 v234, v[56:59], s[52:53] offset:256
	v_mov_b32_e32 v60, v235
	s_waitcnt vmcnt(16)
	v_add_f32_e32 v64, v64, v196
	v_mul_f32_e32 v235, v64, v64
	v_add_f32_e32 v65, v65, v197
	v_fmac_f32_e32 v235, v65, v65
	v_add_f32_e32 v66, v66, v198
	v_fmac_f32_e32 v235, v66, v66
	v_add_f32_e32 v67, v67, v199
	v_fmac_f32_e32 v235, v67, v67
	v_add_f32_e32 v68, v68, v200
	v_fmac_f32_e32 v235, v68, v68
	v_add_f32_e32 v69, v69, v201
	v_fmac_f32_e32 v235, v69, v69
	v_add_f32_e32 v70, v70, v202
	v_fmac_f32_e32 v235, v70, v70
	v_add_f32_e32 v71, v71, v203
	v_fmac_f32_e32 v235, v71, v71
	v_add_f32_e32 v96, v96, v204
	v_fmac_f32_e32 v235, v96, v96
	v_add_f32_e32 v97, v97, v205
	v_fmac_f32_e32 v235, v97, v97
	v_add_f32_e32 v98, v98, v206
	v_fmac_f32_e32 v235, v98, v98
	v_add_f32_e32 v99, v99, v207
	v_fmac_f32_e32 v235, v99, v99
	v_add_f32_e32 v100, v100, v208
	v_fmac_f32_e32 v235, v100, v100
	v_add_f32_e32 v101, v101, v209
	v_fmac_f32_e32 v235, v101, v101
	v_add_f32_e32 v102, v102, v210
	v_fmac_f32_e32 v235, v102, v102
	v_add_f32_e32 v103, v103, v211
	v_fmac_f32_e32 v235, v103, v103
	v_add_u32_e32 v234, 0x80000, v229
	v_cvt_pk_bf16_f32 v64, v64, v65
	v_cvt_pk_bf16_f32 v65, v66, v67
	v_cvt_pk_bf16_f32 v66, v68, v69
	v_cvt_pk_bf16_f32 v67, v70, v71
	s_nop 1
	global_store_dwordx4 v234, v[64:67], s[52:53] offset:0
	v_cvt_pk_bf16_f32 v96, v96, v97
	v_cvt_pk_bf16_f32 v97, v98, v99
	v_cvt_pk_bf16_f32 v98, v100, v101
	v_cvt_pk_bf16_f32 v99, v102, v103
	s_nop 1
	global_store_dwordx4 v234, v[96:99], s[52:53] offset:256
	v_mov_b32_e32 v100, v235
	v_add_f32_e32 v72, v72, v212
	v_mul_f32_e32 v235, v72, v72
	v_add_f32_e32 v73, v73, v213
	v_fmac_f32_e32 v235, v73, v73
	v_add_f32_e32 v74, v74, v214
	v_fmac_f32_e32 v235, v74, v74
	v_add_f32_e32 v75, v75, v215
	v_fmac_f32_e32 v235, v75, v75
	v_add_f32_e32 v76, v76, v216
	v_fmac_f32_e32 v235, v76, v76
	v_add_f32_e32 v77, v77, v217
	v_fmac_f32_e32 v235, v77, v77
	v_add_f32_e32 v78, v78, v218
	v_fmac_f32_e32 v235, v78, v78
	v_add_f32_e32 v79, v79, v219
	v_fmac_f32_e32 v235, v79, v79
	v_add_f32_e32 v104, v104, v220
	v_fmac_f32_e32 v235, v104, v104
	v_add_f32_e32 v105, v105, v221
	v_fmac_f32_e32 v235, v105, v105
	v_add_f32_e32 v106, v106, v222
	v_fmac_f32_e32 v235, v106, v106
	v_add_f32_e32 v107, v107, v223
	v_fmac_f32_e32 v235, v107, v107
	v_add_f32_e32 v108, v108, v224
	v_fmac_f32_e32 v235, v108, v108
	v_add_f32_e32 v109, v109, v225
	v_fmac_f32_e32 v235, v109, v109
	v_add_f32_e32 v110, v110, v226
	v_fmac_f32_e32 v235, v110, v110
	v_add_f32_e32 v111, v111, v227
	v_fmac_f32_e32 v235, v111, v111
	v_add_u32_e32 v234, 0x90000, v229
	v_cvt_pk_bf16_f32 v72, v72, v73
	v_cvt_pk_bf16_f32 v73, v74, v75
	v_cvt_pk_bf16_f32 v74, v76, v77
	v_cvt_pk_bf16_f32 v75, v78, v79
	s_nop 1
	global_store_dwordx4 v234, v[72:75], s[52:53] offset:0
	v_cvt_pk_bf16_f32 v104, v104, v105
	v_cvt_pk_bf16_f32 v105, v106, v107
	v_cvt_pk_bf16_f32 v106, v108, v109
	v_cvt_pk_bf16_f32 v107, v110, v111
	s_nop 1
	global_store_dwordx4 v234, v[104:107], s[52:53] offset:256
	v_mov_b32_e32 v108, v235
	s_waitcnt vmcnt(8)
;     __device__ __forceinline__ void operator()(const f32x4 (&acc)[2][2][4][2], const Unit& u, int wr, int wc, int fr, int fq) const {
;     ...
;                     s += __shfl_xor(s, 16); s += __shfl_xor(s, 32);
;                     if (fq == 0) atomicAdd(ss + row, s); }
;         } else {
;             f32x4 qa0[2][2], qa1[2][2], qb0[2][2], qb1[2][2];
;     ...
;             EPI_LDQ(qa0, qa1, 0); EPI_LDQ(qb0, qb1, 1); asm volatile("" ::: "memory");
;             EPI_DOQ(qa0, qa1, 0); EPI_LDQ(qa0, qa1, 2); asm volatile("" ::: "memory");
;             EPI_DOQ(qb0, qb1, 1); EPI_LDQ(qb0, qb1, 3); asm volatile("" ::: "memory");
;             EPI_DOQ(qa0, qa1, 2); asm volatile("" ::: "memory");
;             EPI_DOQ(qb0, qb1, 3);
; template <class Epi, class Sched, bool ALIGN_EPI = false, bool SP2 = false>
; __device__ __forceinline__ void gemm_phase(PG8_LAS unsigned char* lds, const Gemm g, const Sched& S, const Epi& E) {
;     ...
;         if constexpr (!Epi::AFTER_DRAIN) { E(acc, cur, wr, wc, fr, fq); S.done(cur); }
;         if (!has_next) break;
; #pragma unroll
;         for (int a = 0; a < 2; ++a)
; #pragma unroll
;             for (int b = 0; b < 2; ++b)
; #pragma unroll
;                 for (int m = 0; m < 4; ++m)
; #pragma unroll
;                     for (int n = 0; n < 2; ++n) acc[a][b][m][n] = (f32x4){0.f, 0.f, 0.f, 0.f};
;         cur = nxt; cA = nA; cB = nB; ++ui;
	v_add_f32_e32 v80, v80, v128
	v_mul_f32_e32 v235, v80, v80
	v_add_f32_e32 v81, v81, v129
	v_fmac_f32_e32 v235, v81, v81
	v_add_f32_e32 v82, v82, v130
	v_fmac_f32_e32 v235, v82, v82
	v_add_f32_e32 v83, v83, v131
	v_fmac_f32_e32 v235, v83, v83
	v_add_f32_e32 v84, v84, v132
	v_fmac_f32_e32 v235, v84, v84
	v_add_f32_e32 v85, v85, v133
	v_fmac_f32_e32 v235, v85, v85
	v_add_f32_e32 v86, v86, v134
	v_fmac_f32_e32 v235, v86, v86
	v_add_f32_e32 v87, v87, v135
	v_fmac_f32_e32 v235, v87, v87
	v_add_f32_e32 v112, v112, v136
	v_fmac_f32_e32 v235, v112, v112
	v_add_f32_e32 v113, v113, v137
	v_fmac_f32_e32 v235, v113, v113
	v_add_f32_e32 v114, v114, v138
	v_fmac_f32_e32 v235, v114, v114
	v_add_f32_e32 v115, v115, v139
	v_fmac_f32_e32 v235, v115, v115
	v_add_f32_e32 v116, v116, v140
	v_fmac_f32_e32 v235, v116, v116
	v_add_f32_e32 v117, v117, v141
	v_fmac_f32_e32 v235, v117, v117
	v_add_f32_e32 v118, v118, v142
	v_fmac_f32_e32 v235, v118, v118
	v_add_f32_e32 v119, v119, v143
	v_fmac_f32_e32 v235, v119, v119
	v_add_u32_e32 v234, 0xa0000, v229
	v_cvt_pk_bf16_f32 v80, v80, v81
	v_cvt_pk_bf16_f32 v81, v82, v83
	v_cvt_pk_bf16_f32 v82, v84, v85
	v_cvt_pk_bf16_f32 v83, v86, v87
	s_nop 1
	global_store_dwordx4 v234, v[80:83], s[52:53] offset:0
	v_cvt_pk_bf16_f32 v112, v112, v113
	v_cvt_pk_bf16_f32 v113, v114, v115
	v_cvt_pk_bf16_f32 v114, v116, v117
	v_cvt_pk_bf16_f32 v115, v118, v119
	s_nop 1
	global_store_dwordx4 v234, v[112:115], s[52:53] offset:256
	v_mov_b32_e32 v116, v235
	v_add_f32_e32 v88, v88, v144
	v_mul_f32_e32 v235, v88, v88
	v_add_f32_e32 v89, v89, v145
	v_fmac_f32_e32 v235, v89, v89
	v_add_f32_e32 v90, v90, v146
	v_fmac_f32_e32 v235, v90, v90
	v_add_f32_e32 v91, v91, v147
	v_fmac_f32_e32 v235, v91, v91
	v_add_f32_e32 v92, v92, v148
	v_fmac_f32_e32 v235, v92, v92
	v_add_f32_e32 v93, v93, v149
	v_fmac_f32_e32 v235, v93, v93
	v_add_f32_e32 v94, v94, v150
	v_fmac_f32_e32 v235, v94, v94
	v_add_f32_e32 v95, v95, v151
	v_fmac_f32_e32 v235, v95, v95
	v_add_f32_e32 v120, v120, v152
	v_fmac_f32_e32 v235, v120, v120
	v_add_f32_e32 v121, v121, v153
	v_fmac_f32_e32 v235, v121, v121
	v_add_f32_e32 v122, v122, v154
	v_fmac_f32_e32 v235, v122, v122
	v_add_f32_e32 v123, v123, v155
	v_fmac_f32_e32 v235, v123, v123
	v_add_f32_e32 v124, v124, v156
	v_fmac_f32_e32 v235, v124, v124
	v_add_f32_e32 v125, v125, v157
	v_fmac_f32_e32 v235, v125, v125
	v_add_f32_e32 v126, v126, v158
	v_fmac_f32_e32 v235, v126, v126
	v_add_f32_e32 v127, v127, v159
	v_fmac_f32_e32 v235, v127, v127
	v_add_u32_e32 v234, 0xb0000, v229
	v_cvt_pk_bf16_f32 v88, v88, v89
	v_cvt_pk_bf16_f32 v89, v90, v91
	v_cvt_pk_bf16_f32 v90, v92, v93
	v_cvt_pk_bf16_f32 v91, v94, v95
	s_nop 1
	global_store_dwordx4 v234, v[88:91], s[52:53] offset:0
	v_cvt_pk_bf16_f32 v120, v120, v121
	v_cvt_pk_bf16_f32 v121, v122, v123
	v_cvt_pk_bf16_f32 v122, v124, v125
	v_cvt_pk_bf16_f32 v123, v126, v127
	s_nop 1
	global_store_dwordx4 v234, v[120:123], s[52:53] offset:256
	v_mov_b32_e32 v124, v235
	ds_bpermute_b32 v128, v231, v36
	ds_bpermute_b32 v132, v231, v44
	ds_bpermute_b32 v136, v231, v52
	ds_bpermute_b32 v140, v231, v60
	ds_bpermute_b32 v144, v231, v100
	ds_bpermute_b32 v148, v231, v108
	ds_bpermute_b32 v152, v231, v116
	ds_bpermute_b32 v156, v231, v124
	s_waitcnt lgkmcnt(0)
	v_add_f32_e32 v36, v36, v128
	v_add_f32_e32 v44, v44, v132
	v_add_f32_e32 v52, v52, v136
	v_add_f32_e32 v60, v60, v140
	v_add_f32_e32 v100, v100, v144
	v_add_f32_e32 v108, v108, v148
	v_add_f32_e32 v116, v116, v152
	v_add_f32_e32 v124, v124, v156
	ds_bpermute_b32 v128, v232, v36
	ds_bpermute_b32 v132, v232, v44
	ds_bpermute_b32 v136, v232, v52
	ds_bpermute_b32 v140, v232, v60
	ds_bpermute_b32 v144, v232, v100
	ds_bpermute_b32 v148, v232, v108
	ds_bpermute_b32 v152, v232, v116
	ds_bpermute_b32 v156, v232, v124
	s_waitcnt lgkmcnt(0)
	v_add_f32_e32 v36, v36, v128
	v_add_f32_e32 v44, v44, v132
	v_add_f32_e32 v52, v52, v136
	v_add_f32_e32 v60, v60, v140
	v_add_f32_e32 v100, v100, v144
	v_add_f32_e32 v108, v108, v148
	v_add_f32_e32 v116, v116, v152
	v_add_f32_e32 v124, v124, v156
	s_mov_b64 exec, 0xffff
	global_atomic_add_f32 v230, v36, s[50:51] offset:0
	global_atomic_add_f32 v230, v44, s[50:51] offset:64
	global_atomic_add_f32 v230, v52, s[50:51] offset:128
	global_atomic_add_f32 v230, v60, s[50:51] offset:192
	global_atomic_add_f32 v230, v100, s[50:51] offset:512
	global_atomic_add_f32 v230, v108, s[50:51] offset:576
	global_atomic_add_f32 v230, v116, s[50:51] offset:640
	global_atomic_add_f32 v230, v124, s[50:51] offset:704
	s_mov_b64 exec, -1
	s_nop 1
	s_cmp_eq_u32 s19, 0
	s_cbranch_scc1 .Lp4_done
	s_mov_b32 s17, s20
	s_mov_b32 s18, s21
	s_mov_b64 s[22:23], s[26:27]
	s_mov_b64 s[24:25], s[28:29]
	s_add_u32 s16, s16, 1
	s_branch .Lp4_unit

; __device__ __forceinline__ unsigned xb_ld(unsigned* p)              { return __hip_atomic_load(p, __ATOMIC_RELAXED, __HIP_MEMORY_SCOPE_AGENT); }
; __device__ __forceinline__ unsigned xb_add(unsigned* p, unsigned v) { return __hip_atomic_fetch_add(p, v, __ATOMIC_RELAXED, __HIP_MEMORY_SCOPE_AGENT); }
; #define XB_SPIN(cond, bar) do { unsigned _sp = 0; while (cond) { __builtin_amdgcn_s_sleep(1); \
;     if ((++_sp & 255u) == 0u) { if (xb_ld(&(bar)[XB_TMO])) break; if (_sp > XB_SPIN_CAP) { atomicAdd(&(bar)[XB_TMO], 1u); break; } } } } while (0)
; #define GRID_BAR(k) do { if (IN(k) && IN((k) + 1)) xcd_barrier(bar); } while (0)
; __device__ __forceinline__ void xcd_barrier(const XcdBarrier& b) {
;     asm volatile("s_waitcnt vmcnt(0)" ::: "memory");
;     __syncthreads();
;     if (threadIdx.x == 0) {
;         unsigned* bar = b.bar;
;         __builtin_amdgcn_s_waitcnt(0);
;         unsigned nloc = b.st[0], nx = b.st[1];
;         if (nloc == 0u) { xcd_barrier_complete(bar, b.x, nloc, nx); b.st[0] = nloc; b.st[1] = nx; }
;         const unsigned old = xb_add(&bar[XB_XSUB(b.x)], 1u);
;         const unsigned gen = old / nloc;
;         if (old + 1u == (gen + 1u) * nloc) {
;             __builtin_amdgcn_fence(__ATOMIC_RELEASE, "agent");
;             asm volatile("s_waitcnt vmcnt(0)" ::: "memory");
;             const unsigned og = xb_add(&bar[XB_TOP], 1u);
;             const unsigned tg = og / nx;
;             if (og + 1u == (tg + 1u) * nx) xb_add(&bar[XB_TOPGEN], 1u);
;             else XB_SPIN(xb_ld(&bar[XB_TOPGEN]) == tg, bar);
;             __builtin_amdgcn_fence(__ATOMIC_ACQUIRE, "agent");
;             xb_add(&bar[XB_XGEN(b.x)], 1u);
;             asm volatile("s_waitcnt vmcnt(0)" ::: "memory");
;         } else {
;             XB_SPIN(xb_ld(&bar[XB_XGEN(b.x)]) == gen, bar);
;             __builtin_amdgcn_fence(__ATOMIC_ACQUIRE, "agent");
;             asm volatile("s_waitcnt vmcnt(0)" ::: "memory");
;         }
;     }
;     __syncthreads();
; }
; __global__ void __launch_bounds__(NWAVES * 64, 2) hybrid_fwd(Args args) {
;     ...
;     GRID_BAR(4);
.Lp4_exit:
	v_readlane_b32 s40, v253, 60
	v_readlane_b32 s41, v253, 61
	s_nop 3
	s_mov_b32 vcc_lo, s40
	s_mov_b32 vcc_hi, s41
	v_readlane_b32 s4, v253, 0
	v_readlane_b32 s5, v253, 1
	v_readlane_b32 s6, v253, 2
	v_readlane_b32 s7, v253, 3
	v_readlane_b32 s8, v253, 4
	v_readlane_b32 s9, v253, 5
	v_readlane_b32 s10, v253, 6
	v_readlane_b32 s11, v253, 7
	v_readlane_b32 s12, v253, 8
	v_readlane_b32 s13, v253, 9
	v_readlane_b32 s14, v253, 10
	v_readlane_b32 s15, v253, 11
	v_readlane_b32 s16, v253, 12
	v_readlane_b32 s17, v253, 13
	v_readlane_b32 s18, v253, 14
	v_readlane_b32 s19, v253, 15
	v_readlane_b32 s20, v253, 16
	v_readlane_b32 s21, v253, 17
	v_readlane_b32 s22, v253, 18
	v_readlane_b32 s23, v253, 19
	v_readlane_b32 s24, v253, 20
	v_readlane_b32 s25, v253, 21
	v_readlane_b32 s26, v253, 22
	v_readlane_b32 s27, v253, 23
	v_readlane_b32 s28, v253, 24
	v_readlane_b32 s29, v253, 25
	v_readlane_b32 s30, v253, 26
	v_readlane_b32 s31, v253, 27
	v_readlane_b32 s32, v253, 28
	v_readlane_b32 s33, v253, 29
	v_readlane_b32 s34, v253, 30
	v_readlane_b32 s35, v253, 31
	v_readlane_b32 s36, v253, 32
	v_readlane_b32 s37, v253, 33
	v_readlane_b32 s38, v253, 34
	v_readlane_b32 s39, v253, 35
	v_readlane_b32 s40, v253, 36
	v_readlane_b32 s41, v253, 37
	v_readlane_b32 s42, v253, 38
	v_readlane_b32 s43, v253, 39
	v_readlane_b32 s44, v253, 40
	v_readlane_b32 s45, v253, 41
	v_readlane_b32 s46, v253, 42
	v_readlane_b32 s47, v253, 43
	v_readlane_b32 s48, v253, 44
	v_readlane_b32 s49, v253, 45
	v_readlane_b32 s50, v253, 46
	v_readlane_b32 s51, v253, 47
	v_readlane_b32 s52, v253, 48
	v_readlane_b32 s53, v253, 49
	v_readlane_b32 s54, v253, 50
	v_readlane_b32 s55, v253, 51
	v_readlane_b32 s56, v253, 52
	v_readlane_b32 s57, v253, 53
	v_readlane_b32 s58, v253, 54
	v_readlane_b32 s59, v253, 55
	s_nop 7
.LBB0_715:
	s_cmp_gt_i32 s71, 5
	s_cselect_b64 s[0:1], -1, 0
	s_and_b64 s[4:5], s[6:7], s[0:1]
	s_andn2_b64 vcc, exec, s[4:5]
	s_cbranch_vccnz .LBB0_769
	s_waitcnt vmcnt(0)
	s_waitcnt vmcnt(0) lgkmcnt(0)
	s_barrier
	s_and_saveexec_b64 s[4:5], s[96:97]
	s_cbranch_execz .LBB0_768
	s_add_i32 s3, 0, 0x20fc0
	v_mov_b32_e32 v0, s3
	s_waitcnt vmcnt(0) expcnt(0) lgkmcnt(0)
	ds_read_b32 v2, v0
	s_add_i32 s3, 0, 0x20fc4
	v_mov_b32_e32 v0, s3
	ds_read_b32 v0, v0
	s_waitcnt lgkmcnt(1)
	v_cmp_ne_u32_e32 vcc, 0, v2
	s_cbranch_vccnz .LBB0_732
	v_readlane_b32 s6, v244, 4
	v_readlane_b32 s7, v244, 5
	v_readlane_b32 s3, v244, 6
	s_mul_i32 s3, s7, s3
	s_mul_i32 s3, s3, s6
	s_add_u32 s6, s76, 0x20200
	s_addc_u32 s7, s77, 0
	s_add_u32 s8, s76, 0x20400
	s_addc_u32 s9, s77, 0
	s_add_u32 s10, s76, 0x20500
	s_addc_u32 s11, s77, 0
	s_add_u32 s12, s76, 0x20600
	s_addc_u32 s13, s77, 0
	s_add_u32 s14, s76, 0x20700
	s_addc_u32 s15, s77, 0
	s_add_u32 s16, s76, 0x20800
	s_addc_u32 s17, s77, 0
	s_add_u32 s18, s76, 0x20900
	s_addc_u32 s19, s77, 0
	s_add_u32 s20, s76, 0x20a00
	s_addc_u32 s21, s77, 0
	s_add_u32 s22, s76, 0x20b00
	s_addc_u32 s23, s77, 0
	s_add_u32 s24, s76, 0x20c00
	s_addc_u32 s25, s77, 0
	s_add_u32 s26, s76, 0x20d00
	s_addc_u32 s27, s77, 0
	s_add_u32 s28, s76, 0x20e00
	s_addc_u32 s29, s77, 0
	s_add_u32 s30, s76, 0x20f00
	s_addc_u32 s31, s77, 0
	s_add_u32 s34, s76, 0x21000
	s_addc_u32 s35, s77, 0
	s_add_u32 s36, s76, 0x21100
	s_addc_u32 s37, s77, 0
	s_add_u32 s38, s76, 0x21200
	s_addc_u32 s39, s77, 0
	s_add_u32 s40, s76, 0x21300
	s_addc_u32 s41, s77, 0
	s_mov_b32 s33, 1
	v_mov_b32_e32 v16, 0
	s_branch .LBB0_720
